# GEMM tiles: accumulator zeroing replaced by srcC=0 MFMAs in the first K-step (256 v_accvgpr_write per wave per tile removed)
# speedup vs baseline: 1.0637x; 1.0001x over previous
; DEV f32x16 zero16() { float zz = 0.f; asm volatile("" : "+v"(zz)); f32x16 z; for (int i = 0; i < 16; ++i) z[i] = zz; return z; }
; #define ltid() ltid_(swave)
; #define GLOAD(RA, RB, kt) { _Pragma("unroll") for (int i = 0; i < 8; ++i) { const int ia = (tail && i >= 4) ? i - 4 : i; \
;     RA[i] = *(const u32x4*)(abase + ((size_t)(32 * ia) * lda + (kt) * 64) * 2 + aoff); RB[i] = *(const u32x4*)(bbase + ((size_t)(32 * i) * K + (kt) * 64) * 2 + boff); } }
; #define LWRITE(RA, RB, buf) { char* as_ = lds + (buf) * 2 * G_TILE; char* bs_ = as_ + G_TILE; _Pragma("unroll") for (int i = 0; i < 8; ++i) { *(u32x4*)(as_ + (lrow + 32 * i) * GS_B + lch * 16) = RA[i]; *(u32x4*)(bs_ + (lrow + 32 * i) * GS_B + lch * 16) = RB[i]; } }
; template <int EPI>
; DEV void gemm_tile(CParams& p, int layer, const bf16_t* __restrict__ A, int lda, const bf16_t* __restrict__ Bt, int K, int m0, int n0, int nt, char* lds, const int swave) {
;   const int tid = ltid(), lane = tid & 63, w = __builtin_amdgcn_readfirstlane(tid >> 6), wm = w >> 1, wn = w & 1, lr = lane & 31, hh = lane >> 5;
;   const int lrow = tid >> 3, lch = tid & 7;
;   f32x16 acc[4][4];
; #pragma unroll
;   for (int j = 0; j < 4; ++j)
; #pragma unroll
;     for (int i = 0; i < 4; ++i) acc[j][i] = zero16();
;   u32x4 ra0[8], rb0[8], ra1[8], rb1[8];
;   const int nk = K / 64;
;   const char* abase = (const char*)(A + (size_t)m0 * lda);
;   const char* bbase = (const char*)(Bt + (size_t)n0 * K);
;   const unsigned aoff = (unsigned)(lrow * lda + lch * 8) * 2u;
;   const unsigned boff = (unsigned)(lrow * K + lch * 8) * 2u;
;   const bool tail = m0 + 256 > MTOK;
;     ...
;   const char* asr = lds + (wm * 128 + lr) * GS_B + hh * 16;
;   const char* bsr = lds + G_TILE + (wn * 128 + lr) * GS_B + hh * 16;
;   char* wsw = lds + lrow * GS_B + lch * 16;
;     ...
;   GLOAD(ra0, rb0, 0); GLOAD(ra1, rb1, 1); LWRITE(ra0, rb0, 0); __syncthreads();
.LBB0_97:
	s_ashr_i32 s2, s29, 31
	s_lshr_b32 s2, s2, 25
	s_add_i32 s2, s29, s2
	s_ashr_i32 s2, s2, 7
	s_lshl_b32 s8, s29, 8
	s_lshl_b32 s3, s2, 11
	s_and_b32 s8, s8, 0x700
	v_mov_b32_e32 v0, v241
	s_or_b32 s66, s3, s8
	s_lshl_b32 s2, s2, 12
	s_lshl_b32 s3, s29, 5
	s_sub_i32 s2, s3, s2
	v_mbcnt_lo_u32_b32 v0, -1, v0
	s_ashr_i32 s67, s66, 31
	s_and_b32 s8, s2, 0xffffff00
	v_mbcnt_hi_u32_b32 v4, -1, v0
	s_lshl_b64 s[2:3], s[66:67], 11
	v_or_b32_e32 v5, s53, v4
	s_add_u32 s2, s23, s2
	v_lshlrev_b32_e32 v0, 4, v4
	v_ashrrev_i32_e32 v6, 3, v5
	s_addc_u32 s3, s28, s3
	s_ashr_i32 s9, s8, 31
	v_and_b32_e32 v199, 0x70, v0
	s_lshl_b64 s[30:31], s[8:9], 11
	v_lshl_or_b32 v240, v6, 11, v199
	s_add_u32 s56, s15, s30
	v_lshl_add_u64 v[0:1], s[2:3], 0, v[240:241]
	s_addc_u32 s57, s22, s31
	v_add_co_u32_e32 v30, vcc, s12, v0
	v_lshl_add_u64 v[2:3], s[56:57], 0, v[240:241]
	s_nop 0
	v_addc_co_u32_e32 v31, vcc, 0, v1, vcc
	v_add_co_u32_e32 v32, vcc, s12, v2
	v_mov_b32_e32 v67, v241
	s_nop 0
	v_addc_co_u32_e32 v33, vcc, 0, v3, vcc
	v_add_co_u32_e32 v34, vcc, s21, v0
	v_mov_b32_e32 v184, v241
	s_nop 0
	v_addc_co_u32_e32 v35, vcc, 0, v1, vcc
	v_add_co_u32_e32 v36, vcc, s21, v2
	v_mov_b32_e32 v185, v241
	s_nop 0
	v_addc_co_u32_e32 v37, vcc, 0, v3, vcc
	v_add_co_u32_e32 v38, vcc, s14, v0
	v_mov_b32_e32 v186, v241
	s_nop 0
	v_addc_co_u32_e32 v39, vcc, 0, v1, vcc
	v_add_co_u32_e32 v40, vcc, s14, v2
	v_mov_b32_e32 v187, v241
	s_nop 0
	v_addc_co_u32_e32 v41, vcc, 0, v3, vcc
	v_add_co_u32_e32 v42, vcc, s45, v0
	v_mov_b32_e32 v188, v241
	s_nop 0
	v_addc_co_u32_e32 v43, vcc, 0, v1, vcc
	v_add_co_u32_e32 v44, vcc, s45, v2
	v_mov_b32_e32 v189, v241
	s_nop 0
	v_addc_co_u32_e32 v45, vcc, 0, v3, vcc
	v_add_co_u32_e32 v46, vcc, s46, v0
	v_mov_b32_e32 v190, v241
	s_nop 0
	v_addc_co_u32_e32 v47, vcc, 0, v1, vcc
	v_add_co_u32_e32 v48, vcc, s46, v2
	v_mov_b32_e32 v191, v241
	s_nop 0
	v_addc_co_u32_e32 v49, vcc, 0, v3, vcc
	v_add_co_u32_e32 v50, vcc, s47, v0
	v_mov_b32_e32 v192, v241
	s_nop 0
	v_addc_co_u32_e32 v51, vcc, 0, v1, vcc
	v_add_co_u32_e32 v64, vcc, s47, v2
	v_mov_b32_e32 v193, v241
	s_nop 0
	v_addc_co_u32_e32 v65, vcc, 0, v3, vcc
	v_add_co_u32_e32 v172, vcc, s76, v0
	v_mov_b32_e32 v194, v241
	s_nop 0
	v_addc_co_u32_e32 v173, vcc, 0, v1, vcc
	v_add_co_u32_e32 v176, vcc, s76, v2
	v_mov_b32_e32 v195, v241
	v_mov_b32_e32 v196, v241
	v_mov_b32_e32 v197, v241
	v_mov_b32_e32 v198, v241
	v_addc_co_u32_e32 v177, vcc, 0, v3, vcc
	global_load_dwordx4 v[52:55], v240, s[2:3]
	global_load_dwordx4 v[56:59], v240, s[56:57]
	global_load_dwordx4 v[60:63], v[30:31], off
	global_load_dwordx4 v[68:71], v[32:33], off
	global_load_dwordx4 v[72:75], v[34:35], off
	global_load_dwordx4 v[76:79], v[36:37], off
	global_load_dwordx4 v[80:83], v[38:39], off
	global_load_dwordx4 v[84:87], v[40:41], off
	global_load_dwordx4 v[88:91], v[42:43], off
	global_load_dwordx4 v[92:95], v[44:45], off
	global_load_dwordx4 v[96:99], v[46:47], off
	global_load_dwordx4 v[108:111], v[48:49], off
	global_load_dwordx4 v[124:127], v[50:51], off
	global_load_dwordx4 v[144:147], v[64:65], off
	global_load_dwordx4 v[160:163], v[172:173], off
	global_load_dwordx4 v[180:183], v[176:177], off
	global_load_dwordx4 v[100:103], v240, s[2:3] offset:128
	global_load_dwordx4 v[104:107], v240, s[56:57] offset:128
	global_load_dwordx4 v[112:115], v[30:31], off offset:128
	global_load_dwordx4 v[116:119], v[32:33], off offset:128
	global_load_dwordx4 v[120:123], v[34:35], off offset:128
	global_load_dwordx4 v[128:131], v[36:37], off offset:128
	global_load_dwordx4 v[132:135], v[38:39], off offset:128
	global_load_dwordx4 v[136:139], v[40:41], off offset:128
	global_load_dwordx4 v[140:143], v[42:43], off offset:128
	global_load_dwordx4 v[148:151], v[44:45], off offset:128
	global_load_dwordx4 v[152:155], v[46:47], off offset:128
	global_load_dwordx4 v[156:159], v[48:49], off offset:128
	global_load_dwordx4 v[164:167], v[50:51], off offset:128
	global_load_dwordx4 v[168:171], v[64:65], off offset:128
	s_nop 0
	global_load_dwordx4 v[172:175], v[172:173], off offset:128
	s_nop 0
	global_load_dwordx4 v[176:179], v[176:177], off offset:128
	v_readfirstlane_b32 s30, v5
	s_mov_b64 s[38:39], 0x20000
	v_bfe_u32 v66, v4, 5, 1
	v_and_b32_e32 v28, 31, v4
	v_mul_lo_u32 v201, v6, s33
	v_lshl_add_u64 v[4:5], v[0:1], 0, s[38:39]
	s_lshl_b32 s9, s30, 1
	s_lshr_b32 s2, s30, 7
	s_and_b32 s9, s9, 0x80
	s_mulk_i32 s2, 0x4800
	v_lshlrev_b32_e32 v200, 4, v66
	v_lshl_add_u64 v[6:7], v[2:3], 0, s[38:39]
	s_mov_b64 s[38:39], 0x30000
	v_lshl_add_u64 v[10:11], v[2:3], 0, s[38:39]
	v_or_b32_e32 v29, s9, v28
	v_add3_u32 v30, 16, v199, v201
	v_mov_b32_e32 v49, s2
	v_mad_u32_u24 v202, v29, s33, v200
	v_add_u32_e32 v31, 0x7e00, v30
	v_lshl_add_u64 v[8:9], v[0:1], 0, s[38:39]
	s_mov_b64 s[38:39], 0x40000
	v_lshl_add_u64 v[14:15], v[2:3], 0, s[38:39]
	v_mad_u32_u24 v49, v28, s33, v49
	s_mov_b32 s36, 0
	v_lshl_add_u64 v[12:13], v[0:1], 0, s[38:39]
	s_mov_b64 s[38:39], 0x50000
	v_lshl_add_u64 v[18:19], v[2:3], 0, s[38:39]
	s_waitcnt vmcnt(31)
	ds_write_b128 v30, v[52:55]
	s_waitcnt vmcnt(30)
	ds_write_b128 v30, v[56:59] offset:36864
	s_waitcnt vmcnt(29)
	ds_write_b128 v30, v[60:63] offset:4608
	s_waitcnt vmcnt(28)
	ds_write_b128 v30, v[68:71] offset:41472
	s_waitcnt vmcnt(27)
	ds_write_b128 v30, v[72:75] offset:9216
	s_waitcnt vmcnt(26)
	ds_write_b128 v30, v[76:79] offset:46080
	s_waitcnt vmcnt(25)
	ds_write_b128 v30, v[80:83] offset:13824
	s_waitcnt vmcnt(24)
	ds_write_b128 v30, v[84:87] offset:50688
	s_waitcnt vmcnt(23)
	ds_write_b128 v30, v[88:91] offset:18432
	s_waitcnt vmcnt(22)
	ds_write_b128 v30, v[92:95] offset:55296
	s_waitcnt vmcnt(21)
	ds_write_b128 v30, v[96:99] offset:23040
	s_waitcnt vmcnt(20)
	ds_write_b128 v30, v[108:111] offset:59904
	s_waitcnt vmcnt(19)
	ds_write_b128 v30, v[124:127] offset:27648
	s_waitcnt vmcnt(18)
	ds_write_b128 v30, v[144:147] offset:64512
	s_waitcnt vmcnt(17)
	ds_write_b128 v30, v[160:163] offset:32256
	s_waitcnt vmcnt(16)
	ds_write_b128 v31, v[180:183] offset:36864
	v_add3_u32 v30, 16, v201, v199
	v_lshl_add_u64 v[24:25], v[0:1], 0, s[48:49]
	v_lshl_add_u64 v[16:17], v[0:1], 0, s[38:39]
	s_mov_b64 s[38:39], 0x60000
	v_lshl_add_u64 v[22:23], v[2:3], 0, s[38:39]
	v_lshl_add_u64 v[26:27], v[2:3], 0, s[48:49]
	v_lshl_add_u64 v[20:21], v[0:1], 0, s[38:39]
	v_add_u32_e32 v29, 16, v202
	v_add_u32_e32 v31, 0x12000, v30
	v_add_u32_e32 v32, 0x1b000, v30
	v_add_u32_e32 v33, 0x16800, v30
	v_add_u32_e32 v34, 0x1f800, v30
	v_add_u32_e32 v35, 0x17a00, v30
	v_add_u32_e32 v36, 0x20a00, v30
	v_add_u32_e32 v37, 0x14400, v30
	v_add_u32_e32 v38, 0x1d400, v30
	v_add_u32_e32 v39, 0x15600, v30
	v_add_u32_e32 v40, 0x1e600, v30
	v_add_u32_e32 v41, 0x13200, v30
	v_add_u32_e32 v42, 0x1c200, v30
	v_add_u32_e32 v43, 0x18c00, v30
	v_add_u32_e32 v44, 0x21c00, v30
	v_add_u32_e32 v45, 0x19e00, v30
	v_add_u32_e32 v46, 0x22e00, v30
	v_add_u32_e32 v47, 0x10e00, v30
	v_add_u32_e32 v48, s24, v202
	v_add3_u32 v49, v49, v200, 16
	s_waitcnt lgkmcnt(0)
	s_barrier
	s_branch .LBB0_99

; #define GLOAD(RA, RB, kt) { _Pragma("unroll") for (int i = 0; i < 8; ++i) { const int ia = (tail && i >= 4) ? i - 4 : i; \
;     RA[i] = *(const u32x4*)(abase + ((size_t)(32 * ia) * lda + (kt) * 64) * 2 + aoff); RB[i] = *(const u32x4*)(bbase + ((size_t)(32 * i) * K + (kt) * 64) * 2 + boff); } }
; #define LWRITE(RA, RB, buf) { char* as_ = lds + (buf) * 2 * G_TILE; char* bs_ = as_ + G_TILE; _Pragma("unroll") for (int i = 0; i < 8; ++i) { *(u32x4*)(as_ + (lrow + 32 * i) * GS_B + lch * 16) = RA[i]; *(u32x4*)(bs_ + (lrow + 32 * i) * GS_B + lch * 16) = RB[i]; } }
; template <int EPI>
; DEV void gemm_tile(CParams& p, int layer, const bf16_t* __restrict__ A, int lda, const bf16_t* __restrict__ Bt, int K, int m0, int n0, int nt, char* lds, const int swave) {
;     ...
;   GLOAD(ra0, rb0, 0); GLOAD(ra1, rb1, 1); LWRITE(ra0, rb0, 0); __syncthreads();
; #pragma unroll 1
;   for (int kt = 0; kt < nk; kt += 2) {
;     if (kt + 2 < nk) GLOAD(ra0, rb0, kt + 2);
;     COMPUTE(0, ra1, rb1, 1, true);
.LBB0_101:
	s_cmp_eq_u32 s36, 0
	s_cbranch_scc0 .Lzi_i1
	ds_read_b128 v[188:191], v49
	ds_read_b128 v[192:195], v49 offset:4608
	ds_read_b128 v[196:199], v49 offset:9216
	ds_read_b128 v[200:203], v49 offset:13824
	ds_read_b128 v[184:187], v48
	ds_read_b128 v[204:207], v48 offset:4608
	s_waitcnt lgkmcnt(1)
	v_mfma_f32_32x32x16_bf16 a[192:207], v[184:187], v[188:191], 0
	v_mfma_f32_32x32x16_bf16 a[128:143], v[184:187], v[192:195], 0
	v_mfma_f32_32x32x16_bf16 a[64:79], v[184:187], v[196:199], 0
	v_mfma_f32_32x32x16_bf16 a[0:15], v[184:187], v[200:203], 0
	ds_read_b128 v[184:187], v48 offset:9216
	ds_read_b128 v[208:211], v49 offset:32
	ds_read_b128 v[212:215], v49 offset:4640
	s_waitcnt lgkmcnt(3)
	v_mfma_f32_32x32x16_bf16 a[208:223], v[204:207], v[188:191], 0
	v_mfma_f32_32x32x16_bf16 a[144:159], v[204:207], v[192:195], 0
	v_mfma_f32_32x32x16_bf16 a[80:95], v[204:207], v[196:199], 0
	v_mfma_f32_32x32x16_bf16 a[16:31], v[204:207], v[200:203], 0
	ds_read_b128 v[204:207], v48 offset:13824
	ds_read_b128 v[216:219], v49 offset:9248
	ds_read_b128 v[220:223], v49 offset:13856
	s_waitcnt lgkmcnt(5)
	v_mfma_f32_32x32x16_bf16 a[224:239], v[184:187], v[188:191], 0
	v_mfma_f32_32x32x16_bf16 a[160:175], v[184:187], v[192:195], 0
	v_mfma_f32_32x32x16_bf16 a[96:111], v[184:187], v[196:199], 0
	v_mfma_f32_32x32x16_bf16 a[32:47], v[184:187], v[200:203], 0
	ds_read_b128 v[184:187], v48 offset:32
	s_waitcnt lgkmcnt(3)
	v_mfma_f32_32x32x16_bf16 a[240:255], v[204:207], v[188:191], 0
	v_mfma_f32_32x32x16_bf16 a[176:191], v[204:207], v[192:195], 0
	v_mfma_f32_32x32x16_bf16 a[112:127], v[204:207], v[196:199], 0
	v_mfma_f32_32x32x16_bf16 a[48:63], v[204:207], v[200:203], 0
	ds_read_b128 v[204:207], v48 offset:4640
	s_waitcnt vmcnt(31)
	ds_write_b128 v31, v[100:103]
	s_waitcnt vmcnt(30)
	ds_write_b128 v32, v[104:107]
	s_waitcnt vmcnt(29)
	ds_write_b128 v41, v[112:115]
	s_waitcnt vmcnt(28)
	ds_write_b128 v42, v[116:119]
	s_waitcnt lgkmcnt(5)
	v_mfma_f32_32x32x16_bf16 a[192:207], v[184:187], v[208:211], a[192:207]
	v_mfma_f32_32x32x16_bf16 a[128:143], v[184:187], v[212:215], a[128:143]
	v_mfma_f32_32x32x16_bf16 a[64:79], v[184:187], v[216:219], a[64:79]
	v_mfma_f32_32x32x16_bf16 a[0:15], v[184:187], v[220:223], a[0:15]
	ds_read_b128 v[184:187], v48 offset:9248
	ds_read_b128 v[188:191], v49 offset:64
	ds_read_b128 v[192:195], v49 offset:4672
	s_waitcnt lgkmcnt(7)
	v_mfma_f32_32x32x16_bf16 a[208:223], v[204:207], v[208:211], a[208:223]
	v_mfma_f32_32x32x16_bf16 a[144:159], v[204:207], v[212:215], a[144:159]
	v_mfma_f32_32x32x16_bf16 a[80:95], v[204:207], v[216:219], a[80:95]
	v_mfma_f32_32x32x16_bf16 a[16:31], v[204:207], v[220:223], a[16:31]
	ds_read_b128 v[204:207], v48 offset:13856
	ds_read_b128 v[196:199], v49 offset:9280
	ds_read_b128 v[200:203], v49 offset:13888
	s_waitcnt lgkmcnt(5)
	v_mfma_f32_32x32x16_bf16 a[224:239], v[184:187], v[208:211], a[224:239]
	v_mfma_f32_32x32x16_bf16 a[160:175], v[184:187], v[212:215], a[160:175]
	v_mfma_f32_32x32x16_bf16 a[96:111], v[184:187], v[216:219], a[96:111]
	v_mfma_f32_32x32x16_bf16 a[32:47], v[184:187], v[220:223], a[32:47]
	ds_read_b128 v[184:187], v48 offset:64
	s_waitcnt lgkmcnt(3)
	v_mfma_f32_32x32x16_bf16 a[240:255], v[204:207], v[208:211], a[240:255]
	v_mfma_f32_32x32x16_bf16 a[176:191], v[204:207], v[212:215], a[176:191]
	v_mfma_f32_32x32x16_bf16 a[112:127], v[204:207], v[216:219], a[112:127]
	v_mfma_f32_32x32x16_bf16 a[48:63], v[204:207], v[220:223], a[48:63]
	ds_read_b128 v[204:207], v48 offset:4672
	s_waitcnt vmcnt(27)
	ds_write_b128 v37, v[120:123]
	s_waitcnt vmcnt(26)
	ds_write_b128 v38, v[128:131]
	s_waitcnt vmcnt(25)
	ds_write_b128 v39, v[132:135]
	s_waitcnt vmcnt(24)
	ds_write_b128 v40, v[136:139]
	s_waitcnt lgkmcnt(5)
	v_mfma_f32_32x32x16_bf16 a[192:207], v[184:187], v[188:191], a[192:207]
	v_mfma_f32_32x32x16_bf16 a[128:143], v[184:187], v[192:195], a[128:143]
	v_mfma_f32_32x32x16_bf16 a[64:79], v[184:187], v[196:199], a[64:79]
	v_mfma_f32_32x32x16_bf16 a[0:15], v[184:187], v[200:203], a[0:15]
	ds_read_b128 v[184:187], v48 offset:9280
	ds_read_b128 v[208:211], v49 offset:96
	ds_read_b128 v[212:215], v49 offset:4704
	s_waitcnt lgkmcnt(7)
	v_mfma_f32_32x32x16_bf16 a[208:223], v[204:207], v[188:191], a[208:223]
	v_mfma_f32_32x32x16_bf16 a[144:159], v[204:207], v[192:195], a[144:159]
	v_mfma_f32_32x32x16_bf16 a[80:95], v[204:207], v[196:199], a[80:95]
	v_mfma_f32_32x32x16_bf16 a[16:31], v[204:207], v[200:203], a[16:31]
	ds_read_b128 v[204:207], v48 offset:13888
	ds_read_b128 v[216:219], v49 offset:9312
	ds_read_b128 v[220:223], v49 offset:13920
	s_waitcnt lgkmcnt(5)
	v_mfma_f32_32x32x16_bf16 a[224:239], v[184:187], v[188:191], a[224:239]
	v_mfma_f32_32x32x16_bf16 a[160:175], v[184:187], v[192:195], a[160:175]
	v_mfma_f32_32x32x16_bf16 a[96:111], v[184:187], v[196:199], a[96:111]
	v_mfma_f32_32x32x16_bf16 a[32:47], v[184:187], v[200:203], a[32:47]
	ds_read_b128 v[184:187], v48 offset:96
	s_waitcnt lgkmcnt(3)
	v_mfma_f32_32x32x16_bf16 a[240:255], v[204:207], v[188:191], a[240:255]
	v_mfma_f32_32x32x16_bf16 a[176:191], v[204:207], v[192:195], a[176:191]
	v_mfma_f32_32x32x16_bf16 a[112:127], v[204:207], v[196:199], a[112:127]
	v_mfma_f32_32x32x16_bf16 a[48:63], v[204:207], v[200:203], a[48:63]
	ds_read_b128 v[204:207], v48 offset:4704
	s_waitcnt vmcnt(23)
	ds_write_b128 v33, v[140:143]
	s_waitcnt vmcnt(22)
	ds_write_b128 v34, v[148:151]
	s_waitcnt vmcnt(21)
	ds_write_b128 v35, v[152:155]
	s_waitcnt vmcnt(20)
	ds_write_b128 v36, v[156:159]
	s_waitcnt lgkmcnt(5)
	v_mfma_f32_32x32x16_bf16 a[192:207], v[184:187], v[208:211], a[192:207]
	v_mfma_f32_32x32x16_bf16 a[128:143], v[184:187], v[212:215], a[128:143]
	v_mfma_f32_32x32x16_bf16 a[64:79], v[184:187], v[216:219], a[64:79]
	v_mfma_f32_32x32x16_bf16 a[0:15], v[184:187], v[220:223], a[0:15]
	ds_read_b128 v[184:187], v48 offset:9312
	s_waitcnt lgkmcnt(5)
	v_mfma_f32_32x32x16_bf16 a[208:223], v[204:207], v[208:211], a[208:223]
	v_mfma_f32_32x32x16_bf16 a[144:159], v[204:207], v[212:215], a[144:159]
	v_mfma_f32_32x32x16_bf16 a[80:95], v[204:207], v[216:219], a[80:95]
	v_mfma_f32_32x32x16_bf16 a[16:31], v[204:207], v[220:223], a[16:31]
	ds_read_b128 v[204:207], v48 offset:13920
	s_waitcnt lgkmcnt(1)
	v_mfma_f32_32x32x16_bf16 a[224:239], v[184:187], v[208:211], a[224:239]
	v_mfma_f32_32x32x16_bf16 a[160:175], v[184:187], v[212:215], a[160:175]
	v_mfma_f32_32x32x16_bf16 a[96:111], v[184:187], v[216:219], a[96:111]
	v_mfma_f32_32x32x16_bf16 a[32:47], v[184:187], v[220:223], a[32:47]
	s_waitcnt lgkmcnt(0)
	v_mfma_f32_32x32x16_bf16 a[240:255], v[204:207], v[208:211], a[240:255]
	v_mfma_f32_32x32x16_bf16 a[176:191], v[204:207], v[212:215], a[176:191]
	v_mfma_f32_32x32x16_bf16 a[112:127], v[204:207], v[216:219], a[112:127]
	v_mfma_f32_32x32x16_bf16 a[48:63], v[204:207], v[220:223], a[48:63]
	s_waitcnt vmcnt(19)
	ds_write_b128 v43, v[164:167]
	s_waitcnt vmcnt(18)
	ds_write_b128 v44, v[168:171]
	s_waitcnt vmcnt(17)
	ds_write_b128 v45, v[172:175]
	s_waitcnt vmcnt(16)
	ds_write_b128 v46, v[176:179]
	s_branch .LBB0_117

; DEV f32x16 zero16() { float zz = 0.f; asm volatile("" : "+v"(zz)); f32x16 z; for (int i = 0; i < 16; ++i) z[i] = zz; return z; }
; #define ltid() ltid_(swave)
; #define GLOAD(RA, RB, kt) { _Pragma("unroll") for (int i = 0; i < 8; ++i) { const int ia = (tail && i >= 4) ? i - 4 : i; \
;     RA[i] = *(const u32x4*)(abase + ((size_t)(32 * ia) * lda + (kt) * 64) * 2 + aoff); RB[i] = *(const u32x4*)(bbase + ((size_t)(32 * i) * K + (kt) * 64) * 2 + boff); } }
; #define LWRITE(RA, RB, buf) { char* as_ = lds + (buf) * 2 * G_TILE; char* bs_ = as_ + G_TILE; _Pragma("unroll") for (int i = 0; i < 8; ++i) { *(u32x4*)(as_ + (lrow + 32 * i) * GS_B + lch * 16) = RA[i]; *(u32x4*)(bs_ + (lrow + 32 * i) * GS_B + lch * 16) = RB[i]; } }
; template <int EPI>
; DEV void gemm_tile(CParams& p, int layer, const bf16_t* __restrict__ A, int lda, const bf16_t* __restrict__ Bt, int K, int m0, int n0, int nt, char* lds, const int swave) {
;   const int tid = ltid(), lane = tid & 63, w = __builtin_amdgcn_readfirstlane(tid >> 6), wm = w >> 1, wn = w & 1, lr = lane & 31, hh = lane >> 5;
;   const int lrow = tid >> 3, lch = tid & 7;
;   f32x16 acc[4][4];
; #pragma unroll
;   for (int j = 0; j < 4; ++j)
; #pragma unroll
;     for (int i = 0; i < 4; ++i) acc[j][i] = zero16();
;   u32x4 ra0[8], rb0[8], ra1[8], rb1[8];
;   const int nk = K / 64;
;   const char* abase = (const char*)(A + (size_t)m0 * lda);
;   const char* bbase = (const char*)(Bt + (size_t)n0 * K);
;   const unsigned aoff = (unsigned)(lrow * lda + lch * 8) * 2u;
;   const unsigned boff = (unsigned)(lrow * K + lch * 8) * 2u;
;   const bool tail = m0 + 256 > MTOK;
;     ...
;   const char* asr = lds + (wm * 128 + lr) * GS_B + hh * 16;
;   const char* bsr = lds + G_TILE + (wn * 128 + lr) * GS_B + hh * 16;
;   char* wsw = lds + lrow * GS_B + lch * 16;
;     ...
;   GLOAD(ra0, rb0, 0); GLOAD(ra1, rb1, 1); LWRITE(ra0, rb0, 0); __syncthreads();
.LBB0_157:
	s_ashr_i32 s2, s92, 31
	s_lshr_b32 s2, s2, 27
	s_add_i32 s2, s92, s2
	s_and_b32 s3, s2, 0xffffffe0
	s_sub_i32 s3, s92, s3
	v_mov_b32_e32 v0, v241
	s_ashr_i32 s93, s3, 3
	s_lshl_b32 s2, s2, 6
	s_lshl_b32 s3, s92, 8
	s_and_b32 s2, s2, 0xfffff800
	s_and_b32 s3, s3, 0x700
	v_mbcnt_lo_u32_b32 v0, -1, v0
	s_or_b32 s80, s2, s3
	v_mbcnt_hi_u32_b32 v0, -1, v0
	v_or_b32_e32 v2, s53, v0
	s_ashr_i32 s81, s80, 31
	v_readfirstlane_b32 s95, v2
	s_lshl_b64 s[2:3], s[80:81], s89
	s_lshl_b32 s78, s93, 8
	s_bfe_u32 s94, s95, 0x10006
	s_lshl_b64 s[2:3], s[2:3], 1
	s_add_u32 s2, s31, s2
	s_addc_u32 s3, s36, s3
	s_ashr_i32 s79, s78, 31
	s_waitcnt lgkmcnt(0)
	v_and_b32_e32 v1, 31, v0
	v_and_b32_e32 v214, 63, v0
	v_bfe_u32 v215, v0, 5, 1
	s_lshl_b64 s[44:45], s[78:79], s89
	v_lshlrev_b32_e32 v0, 4, v0
	v_ashrrev_i32_e32 v2, 3, v2
	s_lshl_b64 s[44:45], s[44:45], 1
	v_and_b32_e32 v8, 0x70, v0
	s_add_u32 s56, s15, s44
	v_lshl_or_b32 v240, v2, s90, v8
	s_addc_u32 s57, s22, s45
	v_mul_lo_u32 v10, v2, s33
	v_lshl_add_u64 v[2:3], s[2:3], 0, v[240:241]
	v_mov_b32_e32 v160, v241
	v_mov_b32_e32 v161, v241
	v_mov_b32_e32 v162, v241
	v_mov_b32_e32 v163, v241
	v_mov_b32_e32 v164, v241
	v_mov_b32_e32 v165, v241
	v_mov_b32_e32 v166, v241
	v_mov_b32_e32 v167, v241
	v_mov_b32_e32 v168, v241
	v_mov_b32_e32 v169, v241
	v_mov_b32_e32 v170, v241
	v_mov_b32_e32 v31, v241
	v_mov_b32_e32 v30, v241
	v_mov_b32_e32 v29, v241
	v_mov_b32_e32 v28, v241
	v_mov_b32_e32 v27, v241
	v_lshl_add_u64 v[4:5], s[56:57], 0, v[240:241]
	v_lshl_add_u64 v[6:7], v[2:3], 0, s[8:9]
	global_load_dwordx4 v[32:35], v240, s[2:3]
	global_load_dwordx4 v[36:39], v240, s[56:57]
	global_load_dwordx4 v[40:43], v[6:7], off
	v_lshl_add_u64 v[6:7], v[4:5], 0, s[8:9]
	global_load_dwordx4 v[44:47], v[6:7], off
	v_lshl_add_u64 v[6:7], v[2:3], 0, s[66:67]
	global_load_dwordx4 v[48:51], v[6:7], off
	v_lshl_add_u64 v[6:7], v[4:5], 0, s[66:67]
	global_load_dwordx4 v[52:55], v[6:7], off
	v_lshl_add_u64 v[6:7], v[2:3], 0, s[68:69]
	global_load_dwordx4 v[56:59], v[6:7], off
	v_lshl_add_u64 v[6:7], v[4:5], 0, s[68:69]
	global_load_dwordx4 v[60:63], v[6:7], off
	v_lshl_add_u64 v[6:7], v[2:3], 0, s[70:71]
	global_load_dwordx4 v[64:67], v[6:7], off
	v_lshl_add_u64 v[6:7], v[4:5], 0, s[70:71]
	global_load_dwordx4 v[68:71], v[6:7], off
	v_lshl_add_u64 v[6:7], v[2:3], 0, s[72:73]
	global_load_dwordx4 v[72:75], v[6:7], off
	v_lshl_add_u64 v[6:7], v[4:5], 0, s[72:73]
	global_load_dwordx4 v[76:79], v[6:7], off
	v_lshl_add_u64 v[6:7], v[2:3], 0, s[74:75]
	s_lshl_b32 s81, s94, 7
	global_load_dwordx4 v[80:83], v[6:7], off
	v_lshl_add_u64 v[6:7], v[4:5], 0, s[74:75]
	global_load_dwordx4 v[92:95], v[6:7], off
	v_lshl_add_u64 v[6:7], v[2:3], 0, s[76:77]
	global_load_dwordx4 v[100:103], v[6:7], off
	v_lshl_add_u64 v[6:7], v[4:5], 0, s[76:77]
	global_load_dwordx4 v[108:111], v[6:7], off
	global_load_dwordx4 v[84:87], v240, s[2:3] offset:128
	global_load_dwordx4 v[88:91], v240, s[56:57] offset:128
	v_lshlrev_b32_e32 v0, 4, v215
	v_or_b32_e32 v9, s81, v1
	v_add3_u32 v7, 16, v8, v10
	s_add_u32 s44, s2, s8
	s_addc_u32 s45, s3, 0
	global_load_dwordx4 v[96:99], v240, s[44:45] offset:128
	s_add_u32 s44, s56, s8
	s_addc_u32 s45, s57, 0
	global_load_dwordx4 v[104:107], v240, s[44:45] offset:128
	s_add_u32 s44, s2, s66
	s_addc_u32 s45, s3, 0
	global_load_dwordx4 v[112:115], v240, s[44:45] offset:128
	s_add_u32 s44, s56, s66
	s_addc_u32 s45, s57, 0
	global_load_dwordx4 v[116:119], v240, s[44:45] offset:128
	s_add_u32 s44, s2, s68
	s_addc_u32 s45, s3, 0
	global_load_dwordx4 v[120:123], v240, s[44:45] offset:128
	s_add_u32 s44, s56, s68
	s_addc_u32 s45, s57, 0
	global_load_dwordx4 v[124:127], v240, s[44:45] offset:128
	s_add_u32 s44, s2, s70
	s_addc_u32 s45, s3, 0
	global_load_dwordx4 v[128:131], v240, s[44:45] offset:128
	s_add_u32 s44, s56, s70
	s_addc_u32 s45, s57, 0
	global_load_dwordx4 v[132:135], v240, s[44:45] offset:128
	s_add_u32 s44, s2, s72
	s_addc_u32 s45, s3, 0
	global_load_dwordx4 v[136:139], v240, s[44:45] offset:128
	s_add_u32 s44, s56, s72
	s_addc_u32 s45, s57, 0
	global_load_dwordx4 v[140:143], v240, s[44:45] offset:128
	s_add_u32 s44, s2, s74
	s_addc_u32 s45, s3, 0
	global_load_dwordx4 v[144:147], v240, s[44:45] offset:128
	s_add_u32 s44, s56, s74
	s_addc_u32 s45, s57, 0
	global_load_dwordx4 v[148:151], v240, s[44:45] offset:128
	v_mad_u32_u24 v25, v9, s33, v0
	s_mov_b32 s86, 0
	s_add_u32 s2, s2, s76
	s_addc_u32 s3, s3, 0
	global_load_dwordx4 v[152:155], v240, s[2:3] offset:128
	s_add_u32 s2, s56, s76
	s_addc_u32 s3, s57, 0
	global_load_dwordx4 v[156:159], v240, s[2:3] offset:128
	s_lshr_b32 s2, s95, 7
	s_mulk_i32 s2, 0x4800
	v_mov_b32_e32 v26, s2
	v_mad_u32_u24 v26, v1, s33, v26
	v_add_u32_e32 v6, 16, v25
	v_add_u32_e32 v25, s24, v25
	v_add_u32_e32 v9, 0x7e00, v7
	s_waitcnt vmcnt(31)
	ds_write_b128 v7, v[32:35]
	s_waitcnt vmcnt(30)
	ds_write_b128 v7, v[36:39] offset:36864
	s_waitcnt vmcnt(29)
	ds_write_b128 v7, v[40:43] offset:4608
	s_waitcnt vmcnt(28)
	ds_write_b128 v7, v[44:47] offset:41472
	s_waitcnt vmcnt(27)
	ds_write_b128 v7, v[48:51] offset:9216
	s_waitcnt vmcnt(26)
	ds_write_b128 v7, v[52:55] offset:46080
	s_waitcnt vmcnt(25)
	ds_write_b128 v7, v[56:59] offset:13824
	s_waitcnt vmcnt(24)
	ds_write_b128 v7, v[60:63] offset:50688
	s_waitcnt vmcnt(23)
	ds_write_b128 v7, v[64:67] offset:18432
	s_waitcnt vmcnt(22)
	ds_write_b128 v7, v[68:71] offset:55296
	s_waitcnt vmcnt(21)
	ds_write_b128 v7, v[72:75] offset:23040
	s_waitcnt vmcnt(20)
	ds_write_b128 v7, v[76:79] offset:59904
	s_waitcnt vmcnt(19)
	ds_write_b128 v7, v[80:83] offset:27648
	s_waitcnt vmcnt(18)
	ds_write_b128 v7, v[92:95] offset:64512
	s_waitcnt vmcnt(17)
	ds_write_b128 v7, v[100:103] offset:32256
	s_waitcnt vmcnt(16)
	ds_write_b128 v9, v[108:111] offset:36864
	v_add3_u32 v7, 16, v10, v8
	v_add_u32_e32 v24, 0x10e00, v7
	v_add3_u32 v26, v26, v0, 16
	v_add_u32_e32 v8, 0x12000, v7
	v_add_u32_e32 v10, 0x16800, v7
	v_add_u32_e32 v9, 0x1b000, v7
	v_add_u32_e32 v11, 0x1f800, v7
	v_add_u32_e32 v12, 0x17a00, v7
	v_add_u32_e32 v13, 0x20a00, v7
	v_add_u32_e32 v14, 0x14400, v7
	v_add_u32_e32 v15, 0x1d400, v7
	v_add_u32_e32 v16, 0x15600, v7
	v_add_u32_e32 v17, 0x1e600, v7
	v_add_u32_e32 v18, 0x13200, v7
	v_add_u32_e32 v19, 0x1c200, v7
	v_add_u32_e32 v20, 0x18c00, v7
	v_add_u32_e32 v21, 0x21c00, v7
	v_add_u32_e32 v22, 0x19e00, v7
	v_add_u32_e32 v23, 0x22e00, v7
	s_waitcnt lgkmcnt(0)
	s_barrier
	s_branch .LBB0_159

; #define GLOAD(RA, RB, kt) { _Pragma("unroll") for (int i = 0; i < 8; ++i) { const int ia = (tail && i >= 4) ? i - 4 : i; \
;     RA[i] = *(const u32x4*)(abase + ((size_t)(32 * ia) * lda + (kt) * 64) * 2 + aoff); RB[i] = *(const u32x4*)(bbase + ((size_t)(32 * i) * K + (kt) * 64) * 2 + boff); } }
; #define LWRITE(RA, RB, buf) { char* as_ = lds + (buf) * 2 * G_TILE; char* bs_ = as_ + G_TILE; _Pragma("unroll") for (int i = 0; i < 8; ++i) { *(u32x4*)(as_ + (lrow + 32 * i) * GS_B + lch * 16) = RA[i]; *(u32x4*)(bs_ + (lrow + 32 * i) * GS_B + lch * 16) = RB[i]; } }
; template <int EPI>
; DEV void gemm_tile(CParams& p, int layer, const bf16_t* __restrict__ A, int lda, const bf16_t* __restrict__ Bt, int K, int m0, int n0, int nt, char* lds, const int swave) {
;     ...
;   GLOAD(ra0, rb0, 0); GLOAD(ra1, rb1, 1); LWRITE(ra0, rb0, 0); __syncthreads();
; #pragma unroll 1
;   for (int kt = 0; kt < nk; kt += 2) {
;     if (kt + 2 < nk) GLOAD(ra0, rb0, kt + 2);
;     COMPUTE(0, ra1, rb1, 1, true);
.LBB0_161:
	s_cmp_eq_u32 s86, 0
	s_cbranch_scc0 .Lzi_i2
	ds_read_b128 v[164:167], v26
	ds_read_b128 v[168:171], v26 offset:4608
	ds_read_b128 v[172:175], v26 offset:9216
	ds_read_b128 v[176:179], v26 offset:13824
	ds_read_b128 v[160:163], v25
	ds_read_b128 v[180:183], v25 offset:4608
	s_waitcnt lgkmcnt(1)
	v_mfma_f32_32x32x16_bf16 a[96:111], v[160:163], v[164:167], 0
	v_mfma_f32_32x32x16_bf16 a[0:15], v[160:163], v[168:171], 0
	v_mfma_f32_32x32x16_bf16 a[16:31], v[160:163], v[172:175], 0
	v_mfma_f32_32x32x16_bf16 a[32:47], v[160:163], v[176:179], 0
	ds_read_b128 v[160:163], v25 offset:9216
	ds_read_b128 v[184:187], v26 offset:32
	ds_read_b128 v[188:191], v26 offset:4640
	s_waitcnt lgkmcnt(3)
	v_mfma_f32_32x32x16_bf16 a[80:95], v[180:183], v[164:167], 0
	v_mfma_f32_32x32x16_bf16 a[48:63], v[180:183], v[168:171], 0
	v_mfma_f32_32x32x16_bf16 a[64:79], v[180:183], v[172:175], 0
	v_mfma_f32_32x32x16_bf16 a[112:127], v[180:183], v[176:179], 0
	ds_read_b128 v[180:183], v25 offset:13824
	ds_read_b128 v[192:195], v26 offset:9248
	ds_read_b128 v[196:199], v26 offset:13856
	s_waitcnt lgkmcnt(5)
	v_mfma_f32_32x32x16_bf16 a[128:143], v[160:163], v[164:167], 0
	v_mfma_f32_32x32x16_bf16 a[144:159], v[160:163], v[168:171], 0
	v_mfma_f32_32x32x16_bf16 a[160:175], v[160:163], v[172:175], 0
	v_mfma_f32_32x32x16_bf16 a[176:191], v[160:163], v[176:179], 0
	ds_read_b128 v[160:163], v25 offset:32
	s_waitcnt lgkmcnt(3)
	v_mfma_f32_32x32x16_bf16 a[192:207], v[180:183], v[164:167], 0
	v_mfma_f32_32x32x16_bf16 a[208:223], v[180:183], v[168:171], 0
	v_mfma_f32_32x32x16_bf16 a[224:239], v[180:183], v[172:175], 0
	v_mfma_f32_32x32x16_bf16 a[240:255], v[180:183], v[176:179], 0
	ds_read_b128 v[180:183], v25 offset:4640
	s_waitcnt vmcnt(31)
	ds_write_b128 v8, v[84:87]
	s_waitcnt vmcnt(30)
	ds_write_b128 v9, v[88:91]
	s_waitcnt vmcnt(29)
	ds_write_b128 v18, v[96:99]
	s_waitcnt vmcnt(28)
	ds_write_b128 v19, v[104:107]
	s_waitcnt lgkmcnt(5)
	v_mfma_f32_32x32x16_bf16 a[96:111], v[160:163], v[184:187], a[96:111]
	v_mfma_f32_32x32x16_bf16 a[0:15], v[160:163], v[188:191], a[0:15]
	v_mfma_f32_32x32x16_bf16 a[16:31], v[160:163], v[192:195], a[16:31]
	v_mfma_f32_32x32x16_bf16 a[32:47], v[160:163], v[196:199], a[32:47]
	ds_read_b128 v[160:163], v25 offset:9248
	ds_read_b128 v[164:167], v26 offset:64
	ds_read_b128 v[168:171], v26 offset:4672
	s_waitcnt lgkmcnt(7)
	v_mfma_f32_32x32x16_bf16 a[80:95], v[180:183], v[184:187], a[80:95]
	v_mfma_f32_32x32x16_bf16 a[48:63], v[180:183], v[188:191], a[48:63]
	v_mfma_f32_32x32x16_bf16 a[64:79], v[180:183], v[192:195], a[64:79]
	v_mfma_f32_32x32x16_bf16 a[112:127], v[180:183], v[196:199], a[112:127]
	ds_read_b128 v[180:183], v25 offset:13856
	ds_read_b128 v[172:175], v26 offset:9280
	ds_read_b128 v[176:179], v26 offset:13888
	s_waitcnt lgkmcnt(5)
	v_mfma_f32_32x32x16_bf16 a[128:143], v[160:163], v[184:187], a[128:143]
	v_mfma_f32_32x32x16_bf16 a[144:159], v[160:163], v[188:191], a[144:159]
	v_mfma_f32_32x32x16_bf16 a[160:175], v[160:163], v[192:195], a[160:175]
	v_mfma_f32_32x32x16_bf16 a[176:191], v[160:163], v[196:199], a[176:191]
	ds_read_b128 v[160:163], v25 offset:64
	s_waitcnt lgkmcnt(3)
	v_mfma_f32_32x32x16_bf16 a[192:207], v[180:183], v[184:187], a[192:207]
	v_mfma_f32_32x32x16_bf16 a[208:223], v[180:183], v[188:191], a[208:223]
	v_mfma_f32_32x32x16_bf16 a[224:239], v[180:183], v[192:195], a[224:239]
	v_mfma_f32_32x32x16_bf16 a[240:255], v[180:183], v[196:199], a[240:255]
	ds_read_b128 v[180:183], v25 offset:4672
	s_waitcnt vmcnt(27)
	ds_write_b128 v14, v[112:115]
	s_waitcnt vmcnt(26)
	ds_write_b128 v15, v[116:119]
	s_waitcnt vmcnt(25)
	ds_write_b128 v16, v[120:123]
	s_waitcnt vmcnt(24)
	ds_write_b128 v17, v[124:127]
	s_waitcnt lgkmcnt(5)
	v_mfma_f32_32x32x16_bf16 a[96:111], v[160:163], v[164:167], a[96:111]
	v_mfma_f32_32x32x16_bf16 a[0:15], v[160:163], v[168:171], a[0:15]
	v_mfma_f32_32x32x16_bf16 a[16:31], v[160:163], v[172:175], a[16:31]
	v_mfma_f32_32x32x16_bf16 a[32:47], v[160:163], v[176:179], a[32:47]
	ds_read_b128 v[160:163], v25 offset:9280
	ds_read_b128 v[184:187], v26 offset:96
	ds_read_b128 v[188:191], v26 offset:4704
	s_waitcnt lgkmcnt(7)
	v_mfma_f32_32x32x16_bf16 a[80:95], v[180:183], v[164:167], a[80:95]
	v_mfma_f32_32x32x16_bf16 a[48:63], v[180:183], v[168:171], a[48:63]
	v_mfma_f32_32x32x16_bf16 a[64:79], v[180:183], v[172:175], a[64:79]
	v_mfma_f32_32x32x16_bf16 a[112:127], v[180:183], v[176:179], a[112:127]
	ds_read_b128 v[180:183], v25 offset:13888
	ds_read_b128 v[192:195], v26 offset:9312
	ds_read_b128 v[196:199], v26 offset:13920
	s_waitcnt lgkmcnt(5)
	v_mfma_f32_32x32x16_bf16 a[128:143], v[160:163], v[164:167], a[128:143]
	v_mfma_f32_32x32x16_bf16 a[144:159], v[160:163], v[168:171], a[144:159]
	v_mfma_f32_32x32x16_bf16 a[160:175], v[160:163], v[172:175], a[160:175]
	v_mfma_f32_32x32x16_bf16 a[176:191], v[160:163], v[176:179], a[176:191]
	ds_read_b128 v[160:163], v25 offset:96
	s_waitcnt lgkmcnt(3)
	v_mfma_f32_32x32x16_bf16 a[192:207], v[180:183], v[164:167], a[192:207]
	v_mfma_f32_32x32x16_bf16 a[208:223], v[180:183], v[168:171], a[208:223]
	v_mfma_f32_32x32x16_bf16 a[224:239], v[180:183], v[172:175], a[224:239]
	v_mfma_f32_32x32x16_bf16 a[240:255], v[180:183], v[176:179], a[240:255]
	ds_read_b128 v[180:183], v25 offset:4704
	s_waitcnt vmcnt(23)
	ds_write_b128 v10, v[128:131]
	s_waitcnt vmcnt(22)
	ds_write_b128 v11, v[132:135]
	s_waitcnt vmcnt(21)
	ds_write_b128 v12, v[136:139]
	s_waitcnt vmcnt(20)
	ds_write_b128 v13, v[140:143]
	s_waitcnt lgkmcnt(5)
	v_mfma_f32_32x32x16_bf16 a[96:111], v[160:163], v[184:187], a[96:111]
	v_mfma_f32_32x32x16_bf16 a[0:15], v[160:163], v[188:191], a[0:15]
	v_mfma_f32_32x32x16_bf16 a[16:31], v[160:163], v[192:195], a[16:31]
	v_mfma_f32_32x32x16_bf16 a[32:47], v[160:163], v[196:199], a[32:47]
	ds_read_b128 v[160:163], v25 offset:9312
	s_waitcnt lgkmcnt(5)
	v_mfma_f32_32x32x16_bf16 a[80:95], v[180:183], v[184:187], a[80:95]
	v_mfma_f32_32x32x16_bf16 a[48:63], v[180:183], v[188:191], a[48:63]
	v_mfma_f32_32x32x16_bf16 a[64:79], v[180:183], v[192:195], a[64:79]
	v_mfma_f32_32x32x16_bf16 a[112:127], v[180:183], v[196:199], a[112:127]
	ds_read_b128 v[180:183], v25 offset:13920
	s_waitcnt lgkmcnt(1)
	v_mfma_f32_32x32x16_bf16 a[128:143], v[160:163], v[184:187], a[128:143]
	v_mfma_f32_32x32x16_bf16 a[144:159], v[160:163], v[188:191], a[144:159]
	v_mfma_f32_32x32x16_bf16 a[160:175], v[160:163], v[192:195], a[160:175]
	v_mfma_f32_32x32x16_bf16 a[176:191], v[160:163], v[196:199], a[176:191]
	s_waitcnt lgkmcnt(0)
	v_mfma_f32_32x32x16_bf16 a[192:207], v[180:183], v[184:187], a[192:207]
	v_mfma_f32_32x32x16_bf16 a[208:223], v[180:183], v[188:191], a[208:223]
	v_mfma_f32_32x32x16_bf16 a[224:239], v[180:183], v[192:195], a[224:239]
	v_mfma_f32_32x32x16_bf16 a[240:255], v[180:183], v[196:199], a[240:255]
	s_waitcnt vmcnt(19)
	ds_write_b128 v20, v[144:147]
	s_waitcnt vmcnt(18)
	ds_write_b128 v21, v[148:151]
	s_waitcnt vmcnt(17)
	ds_write_b128 v22, v[152:155]
	s_waitcnt vmcnt(16)
	ds_write_b128 v23, v[156:159]
	s_branch .LBB0_177

; DEV f32x16 zero16() { float zz = 0.f; asm volatile("" : "+v"(zz)); f32x16 z; for (int i = 0; i < 16; ++i) z[i] = zz; return z; }
; #define ltid() ltid_(swave)
; #define GLOAD(RA, RB, kt) { _Pragma("unroll") for (int i = 0; i < 8; ++i) { const int ia = (tail && i >= 4) ? i - 4 : i; \
;     RA[i] = *(const u32x4*)(abase + ((size_t)(32 * ia) * lda + (kt) * 64) * 2 + aoff); RB[i] = *(const u32x4*)(bbase + ((size_t)(32 * i) * K + (kt) * 64) * 2 + boff); } }
; #define LWRITE(RA, RB, buf) { char* as_ = lds + (buf) * 2 * G_TILE; char* bs_ = as_ + G_TILE; _Pragma("unroll") for (int i = 0; i < 8; ++i) { *(u32x4*)(as_ + (lrow + 32 * i) * GS_B + lch * 16) = RA[i]; *(u32x4*)(bs_ + (lrow + 32 * i) * GS_B + lch * 16) = RB[i]; } }
; template <int EPI>
; DEV void gemm_tile(CParams& p, int layer, const bf16_t* __restrict__ A, int lda, const bf16_t* __restrict__ Bt, int K, int m0, int n0, int nt, char* lds, const int swave) {
;   const int tid = ltid(), lane = tid & 63, w = __builtin_amdgcn_readfirstlane(tid >> 6), wm = w >> 1, wn = w & 1, lr = lane & 31, hh = lane >> 5;
;   const int lrow = tid >> 3, lch = tid & 7;
;   f32x16 acc[4][4];
; #pragma unroll
;   for (int j = 0; j < 4; ++j)
; #pragma unroll
;     for (int i = 0; i < 4; ++i) acc[j][i] = zero16();
;   u32x4 ra0[8], rb0[8], ra1[8], rb1[8];
;   const int nk = K / 64;
;   const char* abase = (const char*)(A + (size_t)m0 * lda);
;   const char* bbase = (const char*)(Bt + (size_t)n0 * K);
;   const unsigned aoff = (unsigned)(lrow * lda + lch * 8) * 2u;
;   const unsigned boff = (unsigned)(lrow * K + lch * 8) * 2u;
;   const bool tail = m0 + 256 > MTOK;
;     ...
;   const char* asr = lds + (wm * 128 + lr) * GS_B + hh * 16;
;   const char* bsr = lds + G_TILE + (wn * 128 + lr) * GS_B + hh * 16;
;   char* wsw = lds + lrow * GS_B + lch * 16;
;     ...
;   GLOAD(ra0, rb0, 0); GLOAD(ra1, rb1, 1); LWRITE(ra0, rb0, 0); __syncthreads();
.LBB0_917:
	s_mul_hi_i32 s2, s38, 0x4ec4ec4f
	s_lshr_b32 s3, s2, 31
	s_ashr_i32 s2, s2, 5
	s_add_i32 s2, s2, s3
	s_mul_i32 s3, s2, 0xffffff98
	v_mov_b32_e32 v0, v241
	s_add_i32 s3, s3, s38
	s_ashr_i32 s39, s3, 3
	s_lshl_b32 s3, s38, 8
	v_mbcnt_lo_u32_b32 v0, -1, v0
	s_lshl_b32 s2, s2, 11
	s_and_b32 s3, s3, 0x700
	v_mbcnt_hi_u32_b32 v4, -1, v0
	s_or_b32 s4, s2, s3
	v_or_b32_e32 v5, s53, v4
	s_ashr_i32 s5, s4, 31
	v_readfirstlane_b32 s41, v5
	s_lshl_b32 s6, s39, 8
	s_lshr_b32 s40, s41, 6
	s_lshl_b64 s[2:3], s[4:5], 11
	s_add_u32 s2, s30, s2
	v_lshlrev_b32_e32 v0, 4, v4
	v_ashrrev_i32_e32 v6, 3, v5
	s_addc_u32 s3, s31, s3
	s_ashr_i32 s7, s6, 31
	v_and_b32_e32 v44, 0x70, v0
	s_lshl_b64 s[42:43], s[6:7], 11
	v_lshl_or_b32 v240, v6, 11, v44
	s_add_u32 s56, s22, s42
	v_lshl_add_u64 v[0:1], s[2:3], 0, v[240:241]
	s_addc_u32 s57, s23, s43
	v_add_co_u32_e32 v14, vcc, s12, v0
	v_lshl_add_u64 v[2:3], s[56:57], 0, v[240:241]
	s_nop 0
	v_addc_co_u32_e32 v15, vcc, 0, v1, vcc
	v_add_co_u32_e32 v16, vcc, s12, v2
	v_mov_b32_e32 v47, v241
	s_nop 0
	v_addc_co_u32_e32 v17, vcc, 0, v3, vcc
	v_add_co_u32_e32 v18, vcc, s21, v0
	v_mov_b32_e32 v48, v241
	s_nop 0
	v_addc_co_u32_e32 v19, vcc, 0, v1, vcc
	v_add_co_u32_e32 v20, vcc, s21, v2
	v_mov_b32_e32 v50, v241
	s_nop 0
	v_addc_co_u32_e32 v21, vcc, 0, v3, vcc
	v_add_co_u32_e32 v22, vcc, s14, v0
	v_mov_b32_e32 v51, v241
	s_nop 0
	v_addc_co_u32_e32 v23, vcc, 0, v1, vcc
	v_add_co_u32_e32 v24, vcc, s14, v2
	v_mov_b32_e32 v180, v241
	s_nop 0
	v_addc_co_u32_e32 v25, vcc, 0, v3, vcc
	v_add_co_u32_e32 v26, vcc, s45, v0
	v_mov_b32_e32 v181, v241
	s_nop 0
	v_addc_co_u32_e32 v27, vcc, 0, v1, vcc
	v_add_co_u32_e32 v30, vcc, s45, v2
	v_mov_b32_e32 v182, v241
	s_nop 0
	v_addc_co_u32_e32 v31, vcc, 0, v3, vcc
	v_add_co_u32_e32 v32, vcc, s46, v0
	v_mov_b32_e32 v183, v241
	s_nop 0
	v_addc_co_u32_e32 v33, vcc, 0, v1, vcc
	v_add_co_u32_e32 v34, vcc, s46, v2
	v_mov_b32_e32 v184, v241
	s_nop 0
	v_addc_co_u32_e32 v35, vcc, 0, v3, vcc
	v_add_co_u32_e32 v36, vcc, s47, v0
	v_mov_b32_e32 v185, v241
	s_nop 0
	v_addc_co_u32_e32 v37, vcc, 0, v1, vcc
	v_add_co_u32_e32 v38, vcc, s47, v2
	v_mov_b32_e32 v186, v241
	s_nop 0
	v_addc_co_u32_e32 v39, vcc, 0, v3, vcc
	v_add_co_u32_e32 v40, vcc, s76, v0
	v_mov_b32_e32 v187, v241
	s_nop 0
	v_addc_co_u32_e32 v41, vcc, 0, v1, vcc
	v_add_co_u32_e32 v42, vcc, s76, v2
	v_mov_b32_e32 v188, v241
	v_mov_b32_e32 v189, v241
	v_mov_b32_e32 v190, v241
	v_mov_b32_e32 v191, v241
	v_addc_co_u32_e32 v43, vcc, 0, v3, vcc
	global_load_dwordx4 v[52:55], v240, s[2:3]
	global_load_dwordx4 v[56:59], v240, s[56:57]
	global_load_dwordx4 v[60:63], v[14:15], off
	global_load_dwordx4 v[64:67], v[16:17], off
	global_load_dwordx4 v[68:71], v[18:19], off
	global_load_dwordx4 v[72:75], v[20:21], off
	global_load_dwordx4 v[76:79], v[22:23], off
	global_load_dwordx4 v[80:83], v[24:25], off
	global_load_dwordx4 v[84:87], v[26:27], off
	global_load_dwordx4 v[88:91], v[30:31], off
	global_load_dwordx4 v[92:95], v[32:33], off
	global_load_dwordx4 v[112:115], v[34:35], off
	global_load_dwordx4 v[124:127], v[36:37], off
	global_load_dwordx4 v[140:143], v[38:39], off
	global_load_dwordx4 v[152:155], v[40:41], off
	global_load_dwordx4 v[172:175], v[42:43], off
	global_load_dwordx4 v[104:107], v240, s[2:3] offset:128
	global_load_dwordx4 v[108:111], v240, s[56:57] offset:128
	global_load_dwordx4 v[96:99], v[14:15], off offset:128
	global_load_dwordx4 v[100:103], v[16:17], off offset:128
	global_load_dwordx4 v[116:119], v[18:19], off offset:128
	global_load_dwordx4 v[120:123], v[20:21], off offset:128
	global_load_dwordx4 v[128:131], v[22:23], off offset:128
	global_load_dwordx4 v[132:135], v[24:25], off offset:128
	global_load_dwordx4 v[136:139], v[26:27], off offset:128
	global_load_dwordx4 v[144:147], v[30:31], off offset:128
	global_load_dwordx4 v[148:151], v[32:33], off offset:128
	global_load_dwordx4 v[156:159], v[34:35], off offset:128
	global_load_dwordx4 v[160:163], v[36:37], off offset:128
	global_load_dwordx4 v[164:167], v[38:39], off offset:128
	global_load_dwordx4 v[168:171], v[40:41], off offset:128
	global_load_dwordx4 v[176:179], v[42:43], off offset:128
	s_mov_b64 s[60:61], 0x20000
	v_lshrrev_b32_e32 v247, 5, v5
	v_bfe_u32 v246, v5, 5, 1
	v_and_b32_e32 v28, 31, v4
	s_lshl_b32 s5, s41, 1
	v_mul_lo_u32 v46, v6, s33
	v_lshl_add_u64 v[4:5], v[0:1], 0, s[60:61]
	s_lshr_b32 s2, s41, 7
	s_and_b32 s7, s5, 0x80
	v_add3_u32 v30, 16, v44, v46
	s_mulk_i32 s2, 0x4800
	v_lshl_add_u64 v[6:7], v[2:3], 0, s[60:61]
	s_mov_b64 s[60:61], 0x30000
	v_lshl_add_u64 v[10:11], v[2:3], 0, s[60:61]
	v_lshlrev_b32_e32 v45, 4, v246
	v_lshl_add_u64 v[8:9], v[0:1], 0, s[60:61]
	s_mov_b64 s[60:61], 0x40000
	v_or_b32_e32 v29, s7, v28
	v_lshl_add_u64 v[14:15], v[2:3], 0, s[60:61]
	s_waitcnt vmcnt(31)
	ds_write_b128 v30, v[52:55]
	s_waitcnt vmcnt(30)
	ds_write_b128 v30, v[56:59] offset:36864
	s_waitcnt vmcnt(29)
	ds_write_b128 v30, v[60:63] offset:4608
	s_waitcnt vmcnt(28)
	ds_write_b128 v30, v[64:67] offset:41472
	s_waitcnt vmcnt(27)
	ds_write_b128 v30, v[68:71] offset:9216
	s_waitcnt vmcnt(26)
	ds_write_b128 v30, v[72:75] offset:46080
	s_waitcnt vmcnt(25)
	ds_write_b128 v30, v[76:79] offset:13824
	s_waitcnt vmcnt(24)
	ds_write_b128 v30, v[80:83] offset:50688
	s_waitcnt vmcnt(23)
	ds_write_b128 v30, v[84:87] offset:18432
	s_waitcnt vmcnt(22)
	ds_write_b128 v30, v[88:91] offset:55296
	s_waitcnt vmcnt(21)
	ds_write_b128 v30, v[92:95] offset:23040
	s_waitcnt vmcnt(20)
	ds_write_b128 v30, v[112:115] offset:59904
	s_waitcnt vmcnt(19)
	ds_write_b128 v30, v[124:127] offset:27648
	s_waitcnt vmcnt(18)
	ds_write_b128 v30, v[140:143] offset:64512
	v_lshl_add_u64 v[12:13], v[0:1], 0, s[60:61]
	s_mov_b64 s[60:61], 0x50000
	v_add_u32_e32 v31, 0x7e00, v30
	s_waitcnt vmcnt(17)
	ds_write_b128 v30, v[152:155] offset:32256
	s_waitcnt vmcnt(16)
	ds_write_b128 v31, v[172:175] offset:36864
	v_add3_u32 v30, 16, v46, v44
	v_lshl_add_u64 v[18:19], v[2:3], 0, s[60:61]
	v_mad_u32_u24 v49, v29, s33, v45
	s_mov_b32 s42, 0
	v_lshl_add_u64 v[24:25], v[0:1], 0, s[48:49]
	v_mov_b32_e32 v46, s2
	v_mad_u32_u24 v46, v28, s33, v46
	v_lshl_add_u64 v[26:27], v[2:3], 0, s[48:49]
	v_add_u32_e32 v29, 16, v49
	v_add_u32_e32 v31, 0x12000, v30
	v_add_u32_e32 v32, 0x1b000, v30
	v_add_u32_e32 v33, 0x16800, v30
	v_add_u32_e32 v34, 0x1f800, v30
	v_add_u32_e32 v35, 0x17a00, v30
	v_add_u32_e32 v36, 0x20a00, v30
	v_add_u32_e32 v37, 0x14400, v30
	v_add_u32_e32 v38, 0x1d400, v30
	v_add_u32_e32 v39, 0x15600, v30
	v_add_u32_e32 v40, 0x1e600, v30
	v_add_u32_e32 v41, 0x13200, v30
	v_add_u32_e32 v42, 0x1c200, v30
	v_add_u32_e32 v43, 0x18c00, v30
	v_lshl_add_u64 v[16:17], v[0:1], 0, s[60:61]
	s_mov_b64 s[60:61], 0x60000
	v_lshl_add_u64 v[22:23], v[2:3], 0, s[60:61]
	v_add_u32_e32 v44, 0x21c00, v30
	v_lshl_add_u64 v[20:21], v[0:1], 0, s[60:61]
	v_add3_u32 v45, v46, v45, 16
	v_add_u32_e32 v46, 0x19e00, v30
	v_add_u32_e32 v47, 0x22e00, v30
	v_add_u32_e32 v48, 0x10e00, v30
	v_add_u32_e32 v49, s24, v49
	s_waitcnt lgkmcnt(0)
	s_barrier
	s_branch .LBB0_919

; #define GLOAD(RA, RB, kt) { _Pragma("unroll") for (int i = 0; i < 8; ++i) { const int ia = (tail && i >= 4) ? i - 4 : i; \
;     RA[i] = *(const u32x4*)(abase + ((size_t)(32 * ia) * lda + (kt) * 64) * 2 + aoff); RB[i] = *(const u32x4*)(bbase + ((size_t)(32 * i) * K + (kt) * 64) * 2 + boff); } }
; #define LWRITE(RA, RB, buf) { char* as_ = lds + (buf) * 2 * G_TILE; char* bs_ = as_ + G_TILE; _Pragma("unroll") for (int i = 0; i < 8; ++i) { *(u32x4*)(as_ + (lrow + 32 * i) * GS_B + lch * 16) = RA[i]; *(u32x4*)(bs_ + (lrow + 32 * i) * GS_B + lch * 16) = RB[i]; } }
; template <int EPI>
; DEV void gemm_tile(CParams& p, int layer, const bf16_t* __restrict__ A, int lda, const bf16_t* __restrict__ Bt, int K, int m0, int n0, int nt, char* lds, const int swave) {
;     ...
;   GLOAD(ra0, rb0, 0); GLOAD(ra1, rb1, 1); LWRITE(ra0, rb0, 0); __syncthreads();
; #pragma unroll 1
;   for (int kt = 0; kt < nk; kt += 2) {
;     if (kt + 2 < nk) GLOAD(ra0, rb0, kt + 2);
;     COMPUTE(0, ra1, rb1, 1, true);
.LBB0_921:
	s_cmp_eq_u32 s42, 0
	s_cbranch_scc0 .Lzi_i3
	ds_read_b128 v[184:187], v45
	ds_read_b128 v[188:191], v45 offset:4608
	ds_read_b128 v[192:195], v45 offset:9216
	ds_read_b128 v[196:199], v45 offset:13824
	ds_read_b128 v[180:183], v49
	ds_read_b128 v[204:207], v49 offset:4608
	s_waitcnt lgkmcnt(1)
	v_mfma_f32_32x32x16_bf16 a[0:15], v[180:183], v[184:187], 0
	v_mfma_f32_32x32x16_bf16 a[16:31], v[180:183], v[188:191], 0
	v_mfma_f32_32x32x16_bf16 a[32:47], v[180:183], v[192:195], 0
	v_mfma_f32_32x32x16_bf16 a[48:63], v[180:183], v[196:199], 0
	ds_read_b128 v[180:183], v49 offset:9216
	ds_read_b128 v[208:211], v45 offset:32
	ds_read_b128 v[212:215], v45 offset:4640
	s_waitcnt lgkmcnt(3)
	v_mfma_f32_32x32x16_bf16 a[64:79], v[204:207], v[184:187], 0
	v_mfma_f32_32x32x16_bf16 a[80:95], v[204:207], v[188:191], 0
	v_mfma_f32_32x32x16_bf16 a[96:111], v[204:207], v[192:195], 0
	v_mfma_f32_32x32x16_bf16 a[112:127], v[204:207], v[196:199], 0
	ds_read_b128 v[204:207], v49 offset:13824
	ds_read_b128 v[216:219], v45 offset:9248
	ds_read_b128 v[220:223], v45 offset:13856
	s_waitcnt lgkmcnt(5)
	v_mfma_f32_32x32x16_bf16 a[128:143], v[180:183], v[184:187], 0
	v_mfma_f32_32x32x16_bf16 a[144:159], v[180:183], v[188:191], 0
	v_mfma_f32_32x32x16_bf16 a[160:175], v[180:183], v[192:195], 0
	v_mfma_f32_32x32x16_bf16 a[176:191], v[180:183], v[196:199], 0
	ds_read_b128 v[180:183], v49 offset:32
	s_waitcnt lgkmcnt(3)
	v_mfma_f32_32x32x16_bf16 a[192:207], v[204:207], v[184:187], 0
	v_mfma_f32_32x32x16_bf16 a[208:223], v[204:207], v[188:191], 0
	v_mfma_f32_32x32x16_bf16 a[224:239], v[204:207], v[192:195], 0
	v_mfma_f32_32x32x16_bf16 a[240:255], v[204:207], v[196:199], 0
	ds_read_b128 v[204:207], v49 offset:4640
	s_waitcnt vmcnt(31)
	ds_write_b128 v31, v[104:107]
	s_waitcnt vmcnt(30)
	ds_write_b128 v32, v[108:111]
	s_waitcnt vmcnt(29)
	ds_write_b128 v41, v[96:99]
	s_waitcnt vmcnt(28)
	ds_write_b128 v42, v[100:103]
	s_waitcnt lgkmcnt(5)
	v_mfma_f32_32x32x16_bf16 a[0:15], v[180:183], v[208:211], a[0:15]
	v_mfma_f32_32x32x16_bf16 a[16:31], v[180:183], v[212:215], a[16:31]
	v_mfma_f32_32x32x16_bf16 a[32:47], v[180:183], v[216:219], a[32:47]
	v_mfma_f32_32x32x16_bf16 a[48:63], v[180:183], v[220:223], a[48:63]
	ds_read_b128 v[180:183], v49 offset:9248
	ds_read_b128 v[184:187], v45 offset:64
	ds_read_b128 v[188:191], v45 offset:4672
	s_waitcnt lgkmcnt(7)
	v_mfma_f32_32x32x16_bf16 a[64:79], v[204:207], v[208:211], a[64:79]
	v_mfma_f32_32x32x16_bf16 a[80:95], v[204:207], v[212:215], a[80:95]
	v_mfma_f32_32x32x16_bf16 a[96:111], v[204:207], v[216:219], a[96:111]
	v_mfma_f32_32x32x16_bf16 a[112:127], v[204:207], v[220:223], a[112:127]
	ds_read_b128 v[204:207], v49 offset:13856
	ds_read_b128 v[192:195], v45 offset:9280
	ds_read_b128 v[196:199], v45 offset:13888
	s_waitcnt lgkmcnt(5)
	v_mfma_f32_32x32x16_bf16 a[128:143], v[180:183], v[208:211], a[128:143]
	v_mfma_f32_32x32x16_bf16 a[144:159], v[180:183], v[212:215], a[144:159]
	v_mfma_f32_32x32x16_bf16 a[160:175], v[180:183], v[216:219], a[160:175]
	v_mfma_f32_32x32x16_bf16 a[176:191], v[180:183], v[220:223], a[176:191]
	ds_read_b128 v[180:183], v49 offset:64
	s_waitcnt lgkmcnt(3)
	v_mfma_f32_32x32x16_bf16 a[192:207], v[204:207], v[208:211], a[192:207]
	v_mfma_f32_32x32x16_bf16 a[208:223], v[204:207], v[212:215], a[208:223]
	v_mfma_f32_32x32x16_bf16 a[224:239], v[204:207], v[216:219], a[224:239]
	v_mfma_f32_32x32x16_bf16 a[240:255], v[204:207], v[220:223], a[240:255]
	ds_read_b128 v[204:207], v49 offset:4672
	s_waitcnt vmcnt(27)
	ds_write_b128 v37, v[116:119]
	s_waitcnt vmcnt(26)
	ds_write_b128 v38, v[120:123]
	s_waitcnt vmcnt(25)
	ds_write_b128 v39, v[128:131]
	s_waitcnt vmcnt(24)
	ds_write_b128 v40, v[132:135]
	s_waitcnt lgkmcnt(5)
	v_mfma_f32_32x32x16_bf16 a[0:15], v[180:183], v[184:187], a[0:15]
	v_mfma_f32_32x32x16_bf16 a[16:31], v[180:183], v[188:191], a[16:31]
	v_mfma_f32_32x32x16_bf16 a[32:47], v[180:183], v[192:195], a[32:47]
	v_mfma_f32_32x32x16_bf16 a[48:63], v[180:183], v[196:199], a[48:63]
	ds_read_b128 v[180:183], v49 offset:9280
	ds_read_b128 v[208:211], v45 offset:96
	ds_read_b128 v[212:215], v45 offset:4704
	s_waitcnt lgkmcnt(7)
	v_mfma_f32_32x32x16_bf16 a[64:79], v[204:207], v[184:187], a[64:79]
	v_mfma_f32_32x32x16_bf16 a[80:95], v[204:207], v[188:191], a[80:95]
	v_mfma_f32_32x32x16_bf16 a[96:111], v[204:207], v[192:195], a[96:111]
	v_mfma_f32_32x32x16_bf16 a[112:127], v[204:207], v[196:199], a[112:127]
	ds_read_b128 v[204:207], v49 offset:13888
	ds_read_b128 v[216:219], v45 offset:9312
	ds_read_b128 v[220:223], v45 offset:13920
	s_waitcnt lgkmcnt(5)
	v_mfma_f32_32x32x16_bf16 a[128:143], v[180:183], v[184:187], a[128:143]
	v_mfma_f32_32x32x16_bf16 a[144:159], v[180:183], v[188:191], a[144:159]
	v_mfma_f32_32x32x16_bf16 a[160:175], v[180:183], v[192:195], a[160:175]
	v_mfma_f32_32x32x16_bf16 a[176:191], v[180:183], v[196:199], a[176:191]
	ds_read_b128 v[180:183], v49 offset:96
	s_waitcnt lgkmcnt(3)
	v_mfma_f32_32x32x16_bf16 a[192:207], v[204:207], v[184:187], a[192:207]
	v_mfma_f32_32x32x16_bf16 a[208:223], v[204:207], v[188:191], a[208:223]
	v_mfma_f32_32x32x16_bf16 a[224:239], v[204:207], v[192:195], a[224:239]
	v_mfma_f32_32x32x16_bf16 a[240:255], v[204:207], v[196:199], a[240:255]
	ds_read_b128 v[204:207], v49 offset:4704
	s_waitcnt vmcnt(23)
	ds_write_b128 v33, v[136:139]
	s_waitcnt vmcnt(22)
	ds_write_b128 v34, v[144:147]
	s_waitcnt vmcnt(21)
	ds_write_b128 v35, v[148:151]
	s_waitcnt vmcnt(20)
	ds_write_b128 v36, v[156:159]
	s_waitcnt lgkmcnt(5)
	v_mfma_f32_32x32x16_bf16 a[0:15], v[180:183], v[208:211], a[0:15]
	v_mfma_f32_32x32x16_bf16 a[16:31], v[180:183], v[212:215], a[16:31]
	v_mfma_f32_32x32x16_bf16 a[32:47], v[180:183], v[216:219], a[32:47]
	v_mfma_f32_32x32x16_bf16 a[48:63], v[180:183], v[220:223], a[48:63]
	ds_read_b128 v[180:183], v49 offset:9312
	s_waitcnt lgkmcnt(5)
	v_mfma_f32_32x32x16_bf16 a[64:79], v[204:207], v[208:211], a[64:79]
	v_mfma_f32_32x32x16_bf16 a[80:95], v[204:207], v[212:215], a[80:95]
	v_mfma_f32_32x32x16_bf16 a[96:111], v[204:207], v[216:219], a[96:111]
	v_mfma_f32_32x32x16_bf16 a[112:127], v[204:207], v[220:223], a[112:127]
	ds_read_b128 v[204:207], v49 offset:13920
	s_waitcnt lgkmcnt(1)
	v_mfma_f32_32x32x16_bf16 a[128:143], v[180:183], v[208:211], a[128:143]
	v_mfma_f32_32x32x16_bf16 a[144:159], v[180:183], v[212:215], a[144:159]
	v_mfma_f32_32x32x16_bf16 a[160:175], v[180:183], v[216:219], a[160:175]
	v_mfma_f32_32x32x16_bf16 a[176:191], v[180:183], v[220:223], a[176:191]
	s_waitcnt lgkmcnt(0)
	v_mfma_f32_32x32x16_bf16 a[192:207], v[204:207], v[208:211], a[192:207]
	v_mfma_f32_32x32x16_bf16 a[208:223], v[204:207], v[212:215], a[208:223]
	v_mfma_f32_32x32x16_bf16 a[224:239], v[204:207], v[216:219], a[224:239]
	v_mfma_f32_32x32x16_bf16 a[240:255], v[204:207], v[220:223], a[240:255]
	s_waitcnt vmcnt(19)
	ds_write_b128 v43, v[160:163]
	s_waitcnt vmcnt(18)
	ds_write_b128 v44, v[164:167]
	s_waitcnt vmcnt(17)
	ds_write_b128 v46, v[168:171]
	s_waitcnt vmcnt(16)
	ds_write_b128 v47, v[176:179]
	s_branch .LBB0_937
